# R1+C1+AT1: attention loop trimmed: tile loads via scalar base + 32-bit lane offset (no 64-bit VALU address math), redundant v_max(x,x) / 0+x removed in the softmax; bit-identical
# speedup vs baseline: 1.0122x; 1.0010x over previous
.LBB0_629:
	v_max_f32_e32 v148, v84, v85
	v_max3_f32 v148, v148, v86, v87
	v_max3_f32 v148, v148, v88, v89
	v_max3_f32 v148, v148, v90, v91
	v_max3_f32 v148, v148, v92, v93
	v_max3_f32 v148, v148, v94, v95
	v_max3_f32 v148, v148, v96, v97
	v_max3_f32 v148, v148, v98, v99
	v_max3_f32 v148, v148, v68, v69
	v_max3_f32 v148, v148, v70, v71
	v_max3_f32 v148, v148, v72, v73
	v_max3_f32 v148, v148, v74, v75
	v_max3_f32 v148, v148, v76, v77
	v_max3_f32 v148, v148, v78, v79
	v_max3_f32 v148, v148, v80, v81
	v_max3_f32 v148, v148, v82, v83
	v_mov_b32_e32 v149, v148
	s_nop 1
	v_permlane32_swap_b32_e32 v148, v149
	v_max_f32_e32 v148, v148, v149
	v_sub_f32_e32 v149, v148, v182
	v_cmp_ge_f32_e32 vcc, s23, v149
	v_max_f32_e32 v148, v182, v148
	s_cmp_eq_u64 vcc, exec
	s_cselect_b64 vcc, -1, 0
	v_sub_f32_e32 v150, v182, v148
	v_cndmask_b32_e32 v182, v148, v182, vcc
	v_mul_f32_e32 v148, 0xbe0293ee, v182
	v_fmamk_f32 v84, v84, 0x3e0293ee, v148
	v_fmamk_f32 v85, v85, 0x3e0293ee, v148
	v_fmamk_f32 v86, v86, 0x3e0293ee, v148
	v_fmamk_f32 v87, v87, 0x3e0293ee, v148
	v_fmamk_f32 v88, v88, 0x3e0293ee, v148
	v_fmamk_f32 v89, v89, 0x3e0293ee, v148
	v_fmamk_f32 v90, v90, 0x3e0293ee, v148
	v_fmamk_f32 v91, v91, 0x3e0293ee, v148
	v_fmamk_f32 v92, v92, 0x3e0293ee, v148
	v_fmamk_f32 v93, v93, 0x3e0293ee, v148
	v_fmamk_f32 v94, v94, 0x3e0293ee, v148
	v_fmamk_f32 v95, v95, 0x3e0293ee, v148
	v_fmamk_f32 v96, v96, 0x3e0293ee, v148
	v_fmamk_f32 v97, v97, 0x3e0293ee, v148
	v_fmamk_f32 v98, v98, 0x3e0293ee, v148
	v_fmamk_f32 v99, v99, 0x3e0293ee, v148
	v_fmamk_f32 v68, v68, 0x3e0293ee, v148
	v_fmamk_f32 v69, v69, 0x3e0293ee, v148
	v_fmamk_f32 v70, v70, 0x3e0293ee, v148
	v_fmamk_f32 v71, v71, 0x3e0293ee, v148
	v_fmamk_f32 v72, v72, 0x3e0293ee, v148
	v_fmamk_f32 v73, v73, 0x3e0293ee, v148
	v_fmamk_f32 v74, v74, 0x3e0293ee, v148
	v_fmamk_f32 v75, v75, 0x3e0293ee, v148
	v_fmamk_f32 v76, v76, 0x3e0293ee, v148
	v_fmamk_f32 v77, v77, 0x3e0293ee, v148
	v_fmamk_f32 v78, v78, 0x3e0293ee, v148
	v_fmamk_f32 v79, v79, 0x3e0293ee, v148
	v_fmamk_f32 v80, v80, 0x3e0293ee, v148
	v_fmamk_f32 v81, v81, 0x3e0293ee, v148
	v_fmamk_f32 v82, v82, 0x3e0293ee, v148
	v_fmac_f32_e32 v148, 0x3e0293ee, v83
	v_exp_f32_e32 v83, v84
	v_exp_f32_e32 v84, v85
	v_exp_f32_e32 v85, v86
	v_exp_f32_e32 v86, v87
	v_exp_f32_e32 v87, v88
	v_exp_f32_e32 v88, v89
	v_exp_f32_e32 v89, v90
	v_exp_f32_e32 v90, v91
	v_exp_f32_e32 v91, v92
	v_exp_f32_e32 v92, v93
	v_exp_f32_e32 v93, v94
	v_exp_f32_e32 v94, v95
	v_exp_f32_e32 v95, v96
	v_exp_f32_e32 v96, v97
	v_exp_f32_e32 v97, v98
	v_exp_f32_e32 v98, v99
	v_exp_f32_e32 v99, v148
	v_add_f32_e32 v148, v84, v83
	v_add_f32_e32 v148, v85, v148
	v_add_f32_e32 v148, v86, v148
	v_add_f32_e32 v148, v87, v148
	v_add_f32_e32 v148, v88, v148
	v_add_f32_e32 v148, v89, v148
	v_add_f32_e32 v148, v90, v148
	v_add_f32_e32 v148, v91, v148
	v_add_f32_e32 v148, v92, v148
	v_add_f32_e32 v148, v93, v148
	v_add_f32_e32 v148, v94, v148
	v_exp_f32_e32 v68, v68
	v_add_f32_e32 v148, v95, v148
	v_exp_f32_e32 v69, v69
	v_add_f32_e32 v148, v96, v148
	v_exp_f32_e32 v70, v70
	v_add_f32_e32 v148, v97, v148
	v_exp_f32_e32 v71, v71
	v_add_f32_e32 v148, v98, v148
	v_exp_f32_e32 v72, v72
	v_add_f32_e32 v148, v68, v148
	v_exp_f32_e32 v73, v73
	v_add_f32_e32 v148, v69, v148
	v_exp_f32_e32 v74, v74
	v_add_f32_e32 v148, v70, v148
	v_exp_f32_e32 v75, v75
	v_add_f32_e32 v148, v71, v148
	v_exp_f32_e32 v76, v76
	v_add_f32_e32 v148, v72, v148
	v_exp_f32_e32 v77, v77
	v_add_f32_e32 v148, v73, v148
	v_exp_f32_e32 v78, v78
	v_add_f32_e32 v148, v74, v148
	v_exp_f32_e32 v79, v79
	v_add_f32_e32 v148, v75, v148
	v_exp_f32_e32 v80, v80
	v_add_f32_e32 v148, v76, v148
	v_exp_f32_e32 v81, v81
	v_add_f32_e32 v148, v77, v148
	v_exp_f32_e32 v82, v82
	v_add_f32_e32 v148, v78, v148
	v_mul_f32_e32 v150, 0x3e0293ee, v150
	v_add_f32_e32 v148, v79, v148
	v_exp_f32_e32 v150, v150
	v_add_f32_e32 v148, v80, v148
	v_add_f32_e32 v148, v81, v148
	v_add_f32_e32 v148, v82, v148
	v_add_f32_e32 v185, v99, v148
	v_cndmask_b32_e64 v184, v150, 1.0, vcc
	v_mov_b32_e32 v186, v185
	v_cvt_pk_bf16_f32 v148, v83, v84
	v_cvt_pk_bf16_f32 v149, v85, v86
	v_cvt_pk_bf16_f32 v150, v87, v88
	v_cvt_pk_bf16_f32 v151, v89, v90
	v_cvt_pk_bf16_f32 v152, v91, v92
	v_cvt_pk_bf16_f32 v153, v93, v94
	v_cvt_pk_bf16_f32 v154, v95, v96
	v_cvt_pk_bf16_f32 v155, v97, v98
	v_cvt_pk_bf16_f32 v156, v68, v69
	v_cvt_pk_bf16_f32 v157, v70, v71
	v_cvt_pk_bf16_f32 v158, v72, v73
	v_cvt_pk_bf16_f32 v159, v74, v75
	v_cvt_pk_bf16_f32 v160, v76, v77
	v_cvt_pk_bf16_f32 v161, v78, v79
	v_cvt_pk_bf16_f32 v162, v80, v81
	v_cvt_pk_bf16_f32 v163, v82, v99
	s_mov_b32 s53, s52
	s_nop 0
	v_permlane32_swap_b32_e32 v185, v186
	v_permlane32_swap_b32_e32 v148, v150
	v_permlane32_swap_b32_e32 v149, v151
	v_permlane32_swap_b32_e32 v152, v154
	v_permlane32_swap_b32_e32 v153, v155
	v_permlane32_swap_b32_e32 v156, v158
	v_permlane32_swap_b32_e32 v157, v159
	v_permlane32_swap_b32_e32 v160, v162
	v_permlane32_swap_b32_e32 v161, v163
	v_cmp_gt_f32_e32 vcc, 1.0, v184
	s_cbranch_vccz .LBB0_633
	s_and_saveexec_b64 s[16:17], s[38:39]
	ds_write_b32 v172, v184 offset:128
	s_or_b64 exec, exec, s[16:17]
	s_waitcnt lgkmcnt(0)
	v_add_u32_e32 v80, v171, v168
	ds_read_b128 v[68:71], v80 offset:224
	ds_read_b128 v[72:75], v80 offset:192
	ds_read_b128 v[76:79], v80 offset:160
	ds_read_b128 v[80:83], v80 offset:128
	s_waitcnt lgkmcnt(3)
	v_pk_mul_f32 v[16:17], v[16:17], v[68:69]
	s_waitcnt lgkmcnt(2)
	v_pk_mul_f32 v[12:13], v[12:13], v[72:73]
	s_waitcnt lgkmcnt(1)
	v_pk_mul_f32 v[8:9], v[8:9], v[76:77]
	v_pk_mul_f32 v[18:19], v[18:19], v[70:71]
	v_pk_mul_f32 v[14:15], v[14:15], v[74:75]
	v_pk_mul_f32 v[10:11], v[10:11], v[78:79]
	s_waitcnt lgkmcnt(0)
	v_pk_mul_f32 v[6:7], v[6:7], v[82:83]
	v_pk_mul_f32 v[4:5], v[4:5], v[80:81]
	v_pk_mul_f32 v[64:65], v[64:65], v[68:69]
	v_pk_mul_f32 v[60:61], v[60:61], v[72:73]
	v_pk_mul_f32 v[56:57], v[56:57], v[76:77]
	v_pk_mul_f32 v[66:67], v[66:67], v[70:71]
	v_pk_mul_f32 v[62:63], v[62:63], v[74:75]
	v_pk_mul_f32 v[58:59], v[58:59], v[78:79]
	v_pk_mul_f32 v[54:55], v[54:55], v[82:83]
	v_pk_mul_f32 v[52:53], v[52:53], v[80:81]
	v_pk_mul_f32 v[48:49], v[48:49], v[68:69]
	v_pk_mul_f32 v[44:45], v[44:45], v[72:73]
	v_pk_mul_f32 v[40:41], v[40:41], v[76:77]
	v_pk_mul_f32 v[50:51], v[50:51], v[70:71]
	v_pk_mul_f32 v[46:47], v[46:47], v[74:75]
	v_pk_mul_f32 v[42:43], v[42:43], v[78:79]
	v_pk_mul_f32 v[38:39], v[38:39], v[82:83]
	v_pk_mul_f32 v[36:37], v[36:37], v[80:81]
	v_pk_mul_f32 v[32:33], v[32:33], v[68:69]
	v_pk_mul_f32 v[28:29], v[28:29], v[72:73]
	v_pk_mul_f32 v[24:25], v[24:25], v[76:77]
	v_pk_mul_f32 v[34:35], v[34:35], v[70:71]
	v_pk_mul_f32 v[30:31], v[30:31], v[74:75]
	v_pk_mul_f32 v[26:27], v[26:27], v[78:79]
	v_pk_mul_f32 v[22:23], v[22:23], v[82:83]
	v_pk_mul_f32 v[20:21], v[20:21], v[80:81]
.LBB0_633:
	s_waitcnt lgkmcnt(0)
	s_barrier
	v_lshl_add_u32 v187, s53, 14, v173
	ds_read_b64_tr_b16 v[188:189], v187 offset:0
	ds_read_b64_tr_b16 v[190:191], v187 offset:0x800
	ds_read_b64_tr_b16 v[192:193], v187 offset:0x1000
	ds_read_b64_tr_b16 v[194:195], v187 offset:0x1800
	ds_read_b64_tr_b16 v[196:197], v187 offset:0x2000
	ds_read_b64_tr_b16 v[198:199], v187 offset:0x2800
	ds_read_b64_tr_b16 v[200:201], v187 offset:0x3000
	ds_read_b64_tr_b16 v[202:203], v187 offset:0x3800
	s_lshl_b32 s52, s49, 14
	v_add_u32_e32 v208, s52, v174
	ds_read_b128 v[68:71], v208 offset:0
	ds_read_b128 v[72:75], v208 offset:0x2000
	v_add_u32_e32 v209, s52, v175
	ds_read_b128 v[204:207], v209 offset:0
	ds_read_b128 v[216:219], v209 offset:0x2000
	v_add_u32_e32 v210, s52, v176
	ds_read_b128 v[220:223], v210 offset:0
	ds_read_b128 v[224:227], v210 offset:0x2000
	v_add_u32_e32 v211, s52, v177
	ds_read_b128 v[228:231], v211 offset:0
	ds_read_b128 v[232:235], v211 offset:0x2000
	s_waitcnt lgkmcnt(4)
	v_mfma_f32_32x32x16_bf16 v[84:99], v[68:71], v[128:131], 0
	v_mfma_f32_32x32x16_bf16 v[68:83], v[72:75], v[128:131], 0
	v_mfma_f32_32x32x16_bf16 v[84:99], v[204:207], v[124:127], v[84:99]
	v_mfma_f32_32x32x16_bf16 v[68:83], v[216:219], v[124:127], v[68:83]
	ds_read_b128 v[204:207], v208 offset:0x80
	ds_read_b128 v[216:219], v208 offset:0x2080
	ds_read_b128 v[236:239], v209 offset:0x80
	ds_read_b128 v[242:245], v209 offset:0x2080
	s_waitcnt lgkmcnt(4)
	v_mfma_f32_32x32x16_bf16 v[84:99], v[220:223], v[120:123], v[84:99]
	v_mfma_f32_32x32x16_bf16 v[68:83], v[224:227], v[120:123], v[68:83]
	v_mfma_f32_32x32x16_bf16 v[84:99], v[228:231], v[116:119], v[84:99]
	v_mfma_f32_32x32x16_bf16 v[68:83], v[232:235], v[116:119], v[68:83]
	ds_read_b128 v[220:223], v210 offset:0x80
	ds_read_b128 v[224:227], v210 offset:0x2080
	ds_read_b128 v[228:231], v211 offset:0x80
	ds_read_b128 v[232:235], v211 offset:0x2080
	s_waitcnt lgkmcnt(4)
	v_mfma_f32_32x32x16_bf16 v[84:99], v[204:207], v[112:115], v[84:99]
	v_mfma_f32_32x32x16_bf16 v[68:83], v[216:219], v[112:115], v[68:83]
	v_mfma_f32_32x32x16_bf16 v[84:99], v[236:239], v[108:111], v[84:99]
	v_mfma_f32_32x32x16_bf16 v[68:83], v[242:245], v[108:111], v[68:83]
	s_waitcnt lgkmcnt(0)
	v_mfma_f32_32x32x16_bf16 v[84:99], v[220:223], v[104:107], v[84:99]
	v_mfma_f32_32x32x16_bf16 v[68:83], v[224:227], v[104:107], v[68:83]
	v_mfma_f32_32x32x16_bf16 v[84:99], v[228:231], v[100:103], v[84:99]
	v_mfma_f32_32x32x16_bf16 v[68:83], v[232:235], v[100:103], v[68:83]
	ds_read_b64_tr_b16 v[204:205], v187 offset:0x200
	ds_read_b64_tr_b16 v[206:207], v187 offset:0xa00
	ds_read_b64_tr_b16 v[216:217], v187 offset:0x1200
	ds_read_b64_tr_b16 v[218:219], v187 offset:0x1a00
	ds_read_b64_tr_b16 v[220:221], v187 offset:0x2200
	ds_read_b64_tr_b16 v[222:223], v187 offset:0x2a00
	ds_read_b64_tr_b16 v[224:225], v187 offset:0x3200
	ds_read_b64_tr_b16 v[226:227], v187 offset:0x3a00
	s_waitcnt lgkmcnt(8)
	v_mfma_f32_32x32x16_bf16 v[4:19], v[148:151], v[188:191], v[4:19]
	v_mfma_f32_32x32x16_bf16 v[4:19], v[152:155], v[192:195], v[4:19]
	v_mfma_f32_32x32x16_bf16 v[4:19], v[156:159], v[196:199], v[4:19]
	v_mfma_f32_32x32x16_bf16 v[4:19], v[160:163], v[200:203], v[4:19]
	ds_read_b64_tr_b16 v[188:189], v187 offset:0x400
	ds_read_b64_tr_b16 v[190:191], v187 offset:0xc00
	ds_read_b64_tr_b16 v[192:193], v187 offset:0x1400
	ds_read_b64_tr_b16 v[194:195], v187 offset:0x1c00
	ds_read_b64_tr_b16 v[196:197], v187 offset:0x2400
	ds_read_b64_tr_b16 v[198:199], v187 offset:0x2c00
	ds_read_b64_tr_b16 v[200:201], v187 offset:0x3400
	ds_read_b64_tr_b16 v[202:203], v187 offset:0x3c00
	s_waitcnt lgkmcnt(8)
	v_mfma_f32_32x32x16_bf16 v[52:67], v[148:151], v[204:207], v[52:67]
	v_mfma_f32_32x32x16_bf16 v[52:67], v[152:155], v[216:219], v[52:67]
	v_mfma_f32_32x32x16_bf16 v[52:67], v[156:159], v[220:223], v[52:67]
	v_mfma_f32_32x32x16_bf16 v[52:67], v[160:163], v[224:227], v[52:67]
	ds_read_b64_tr_b16 v[204:205], v187 offset:0x600
	ds_read_b64_tr_b16 v[206:207], v187 offset:0xe00
	ds_read_b64_tr_b16 v[216:217], v187 offset:0x1600
	ds_read_b64_tr_b16 v[218:219], v187 offset:0x1e00
	ds_read_b64_tr_b16 v[220:221], v187 offset:0x2600
	ds_read_b64_tr_b16 v[222:223], v187 offset:0x2e00
	ds_read_b64_tr_b16 v[224:225], v187 offset:0x3600
	ds_read_b64_tr_b16 v[226:227], v187 offset:0x3e00
	s_waitcnt lgkmcnt(8)
	v_mfma_f32_32x32x16_bf16 v[36:51], v[148:151], v[188:191], v[36:51]
	v_mfma_f32_32x32x16_bf16 v[36:51], v[152:155], v[192:195], v[36:51]
	v_mfma_f32_32x32x16_bf16 v[36:51], v[156:159], v[196:199], v[36:51]
	v_mfma_f32_32x32x16_bf16 v[36:51], v[160:163], v[200:203], v[36:51]
	s_waitcnt lgkmcnt(0)
	v_mfma_f32_32x32x16_bf16 v[20:35], v[148:151], v[204:207], v[20:35]
	v_mfma_f32_32x32x16_bf16 v[20:35], v[152:155], v[216:219], v[20:35]
	v_mfma_f32_32x32x16_bf16 v[20:35], v[156:159], v[220:223], v[20:35]
	v_mfma_f32_32x32x16_bf16 v[20:35], v[160:163], v[224:227], v[20:35]
	s_lshl_b32 s19, s51, 14
	s_add_i32 s8, s19, 0
	v_add_u32_e32 v148, s8, v179
	s_waitcnt vmcnt(0)
	s_waitcnt vmcnt(0)
	ds_write_b128 v148, v[144:147]
	v_add_u32_e32 v148, s8, v178
	ds_write_b128 v148, v[136:139]
	v_add_u32_e32 v148, s8, v180
	s_add_i32 s48, s48, 1
	ds_write_b128 v148, v[140:143] offset:49152
	v_add_u32_e32 v148, s8, v181
	s_cmp_ge_u32 s48, s46
	ds_write_b128 v148, v[132:135] offset:49152
	s_cbranch_scc1 .LBB0_635
	s_sub_i32 s8, s50, s47
	s_min_u32 s36, s50, s8
	s_lshl_b64 s[8:9], s[36:37], 10
	s_cmp_lt_u32 s50, s47
	s_cselect_b32 s16, s30, s20
	s_cselect_b32 s17, s31, s21
	s_cselect_b32 s36, s42, s26
	s_cselect_b32 s54, s43, s27
	s_add_u32 s16, s16, s8
	s_addc_u32 s17, s17, s9
	s_add_u32 s8, s36, s8
	s_addc_u32 s9, s54, s9
	global_load_dwordx4 v[144:147], v2, s[8:9]
	s_add_u32 s8, s8, 0x8000
	s_addc_u32 s9, s9, 0
	global_load_dwordx4 v[136:139], v2, s[8:9]
	global_load_dwordx4 v[140:143], v2, s[16:17]
	s_add_u32 s16, s16, 0x8000
	s_addc_u32 s17, s17, 0
	global_load_dwordx4 v[132:135], v2, s[16:17]
